# baseline (speedup 1.0000x reference)
; #define LAS __attribute__((address_space(3)))
;     __device__ __forceinline__ const float* in(int i) const { return (const float*)(const __attribute__((address_space(1))) float*)ka[i]; }
; __device__ __forceinline__ void phase_branch(const KP2& p, int l, LAS unsigned char* lds) {
;     ...
;             const float* cw = p.in(I_CCW) + (size_t)l * 3 * BW;
;             LAS unsigned char* pl = lds;
;             for (int idx = tid; idx < R * 32; idx += 512) {
;                 const int i = idx >> 5, c8 = (idx & 31) * 8; const size_t grow = (size_t)(row0 + i);
.LBB0_438:
	s_lshl_b32 s35, s54, 5
	v_cmp_gt_i32_e32 vcc, s35, v68
	s_and_saveexec_b64 s[16:17], vcc
	s_cbranch_execz .LBB0_524
	s_load_dwordx2 s[10:11], s[0:1], 0x98
	s_mul_i32 s12, s88, 0xc00
	s_mov_b64 s[60:61], 0
	v_and_b32_e32 v167, 0x78, v68
	v_lshlrev_b32_e32 v167, 2, v167
	v_lshrrev_b32_e32 v166, 4, v68
	v_and_b32_e32 v166, 0x18, v166
	v_or_b32_e32 v167, v167, v166
	v_and_b32_e32 v166, 7, v68
	v_or_b32_e32 v167, v167, v166
	v_lshlrev_b32_e32 v166, 3, v167
	s_waitcnt lgkmcnt(0)
	s_add_u32 s44, s10, s12
	s_mul_hi_u32 s10, s88, 0xc00
	s_addc_u32 s45, s11, s10
	s_add_i32 s10, s72, s39
	s_sub_i32 s12, s10, s59
	s_ashr_i32 s11, s10, 31
	s_ashr_i32 s13, s12, 31
	s_sub_i32 s43, 0, s43
	s_add_i32 s74, s54, -2
	s_lshl_b64 s[46:47], s[10:11], 11
	s_lshl_b64 s[48:49], s[12:13], 9
	s_add_u32 s13, s48, 0x2978000
	s_addc_u32 s34, s49, 0
	s_lshl_b64 s[48:49], s[10:11], 9
	s_add_u32 s48, s48, 0x2bac000
	s_addc_u32 s49, s49, 0
	s_add_i32 s75, s54, -15
	s_add_i32 s38, s5, -1
	s_mul_i32 s56, s10, 15
	s_mul_hi_i32 s55, s10, 15
	s_and_b64 s[10:11], exec, s[22:23]
	s_cselect_b32 s11, s49, s34
	s_cselect_b32 s10, s48, s13
	s_lshl_b64 s[10:11], s[10:11], 2
	s_add_u32 s48, s20, s10
	s_addc_u32 s49, s21, s11
	s_and_b64 s[10:11], exec, s[22:23]
	s_mov_b32 s10, 0xaef0000
	s_mul_i32 s54, s12, 15
	s_mul_hi_i32 s12, s12, 15
	s_cselect_b32 s10, s10, 0xa600000
	s_cselect_b32 s55, s55, s12
	s_cselect_b32 s54, s56, s54
	s_add_u32 s56, s20, s10
	s_addc_u32 s57, s21, 0
	s_add_i32 s10, s79, s72
	s_mul_hi_i32 s58, s10, 0x3c00
	s_mul_i32 s34, s10, 0x3c00
	s_branch .LBB0_441
